# bias table in LDS loaded once per unit loop (same head for every unit of a CU) instead of per unit
# speedup vs baseline: 1.0003x; 1.0003x over previous
.LBB0_593:
	s_load_dwordx2 s[6:7], s[78:79], 0xb8
	s_load_dwordx2 s[0:1], s[78:79], 0x68
	v_readlane_b32 s2, v255, 10
	v_readlane_b32 s3, v255, 11
	s_mov_b32 s3, s73
	s_waitcnt lgkmcnt(0)
	s_add_u32 s18, s6, 0x13900000
	s_addc_u32 s19, s7, 0
	s_add_u32 s4, s6, 0x1c900000
	v_writelane_b32 v255, s4, 18
	s_addc_u32 s4, s7, 0
	v_writelane_b32 v255, s4, 19
	s_add_u32 s4, s6, 0x1f900000
	s_addc_u32 s5, s7, 0
	v_writelane_b32 v255, s4, 20
	s_movk_i32 s81, 0x1800
	s_mov_b32 s91, 0x38e38e39
	v_writelane_b32 v255, s5, 21
	s_mov_b32 s4, s2
	v_writelane_b32 v255, s4, 10
	s_lshl_b64 s[2:3], s[2:3], 2
	s_add_u32 s2, s6, s2
	v_writelane_b32 v255, s5, 11
	v_writelane_b32 v255, s6, 22
	s_addc_u32 s3, s7, s3
	global_load_dwordx2 v[144:145], v215, s[2:3] offset:128
	s_lshl_b32 s72, s62, 7
	s_lshl_b64 s[2:3], s[72:73], 2
	v_writelane_b32 v255, s7, 23
	s_add_u32 s30, s0, s2
	s_addc_u32 s31, s1, s3
	v_writelane_b32 v255, s76, 24
	s_cmpk_gt_i32 s76, 0x1ff
	v_writelane_b32 v255, s8, 25
	s_waitcnt vmcnt(0)
	v_sub_f32_e32 v145, 1.0, v145
	s_cbranch_scc1 .LBB0_654
	v_readlane_b32 s0, v255, 22
	v_readlane_b32 s1, v255, 23
	s_add_u32 s2, s0, 0x1c900180
	v_writelane_b32 v255, s2, 26
	s_addc_u32 s2, s1, 0
	v_writelane_b32 v255, s2, 27
	s_lshl_b32 s2, s8, 4
	v_readlane_b32 s89, v255, 24
	s_lshl_b32 s83, s89, 4
	v_writelane_b32 v255, s2, 28
	s_add_u32 s0, s0, 0x13a20880
	v_writelane_b32 v255, s0, 29
	s_addc_u32 s0, s1, 0
	v_writelane_b32 v255, s0, 30
	s_lshl_b32 s0, s8, 7
	s_lshl_b32 s90, s89, 7
	v_writelane_b32 v255, s0, 31
	s_mov_b32 s0, 0
	s_nop 0
	v_writelane_b32 v255, s0, 40
	s_branch .LBB0_596

.LBB0_596:
	s_bfe_u32 s2, s89, 0x30005
	v_mov_b32_e32 v141, v210
	s_mul_i32 s6, s2, 0x104
	v_readfirstlane_b32 s4, v141
	v_readlane_b32 s0, v255, 40
	s_cmp_lg_u32 s0, 0
	s_cbranch_scc1 .Lattn_bt_skip_p
	s_mov_b32 s0, 1
	s_nop 0
	v_writelane_b32 v255, s0, 40
	s_movk_i32 s0, 0x1c0
	v_cmp_gt_i32_e32 vcc, s0, v141
	s_and_saveexec_b64 s[0:1], vcc
	s_cbranch_execz .LBB0_598
	v_lshl_add_u32 v0, v141, 2, 0
	v_add_u32_e32 v2, 0x20000, v0
	v_add_u32_e32 v0, 0xffffffa0, v141
	v_max_i32_e32 v0, 0, v0
	v_min_i32_e32 v0, 0x100, v0
	v_add_u32_e32 v0, s6, v0
	v_readlane_b32 s8, v255, 22
	v_ashrrev_i32_e32 v1, 31, v0
	v_readlane_b32 s9, v255, 23
	s_nop 1
	v_lshl_add_u64 v[0:1], v[0:1], 2, s[8:9]
	global_load_dword v0, v[0:1], off
	s_waitcnt vmcnt(0)
	ds_write_b32 v2, v0

.Lattn_bt_skip_p:
	s_lshl_b32 s0, s89, 4
	s_and_b32 s34, s0, 0xfffff000
	s_lshl_b32 s0, s89, 7
	s_and_b32 s5, s0, 0xf80
	s_ashr_i32 s3, s4, 6
	s_lshl_b32 s0, s6, 2
	s_and_b32 s95, s3, 3
	v_and_b32_e32 v140, 31, v141
	v_mov_b32_e32 v2, s0
	s_or_b32 s0, s5, s34
	s_lshl_b32 s88, s95, 5
	v_or_b32_e32 v0, s0, v140
	v_or_b32_e32 v3, s88, v0
	v_mov_b64_e32 v[0:1], s[18:19]
	s_ashr_i32 s58, s4, 8
	v_mad_i64_i32 v[0:1], s[0:1], v3, s81, v[0:1]
	s_lshl_b32 s72, s2, 8
	s_lshl_b32 s0, s58, 6
	v_lshl_add_u64 v[0:1], v[0:1], 0, s[72:73]
	s_ashr_i32 s1, s0, 31
	v_bfe_u32 v158, v141, 5, 1
	v_lshl_add_u64 v[0:1], s[0:1], 1, v[0:1]
	v_readlane_b32 s0, v255, 22
	v_lshlrev_b32_e32 v146, 4, v158
	v_mov_b32_e32 v147, v177
	v_readlane_b32 s1, v255, 23
	v_lshl_add_u64 v[0:1], v[0:1], 0, v[146:147]
	s_nop 3
	global_load_dword v159, v2, s[0:1]
	global_load_dword v160, v2, s[0:1] offset:1024
	global_load_dwordx4 v[112:115], v[0:1], off
	global_load_dwordx4 v[116:119], v[0:1], off offset:32
	global_load_dwordx4 v[120:123], v[0:1], off offset:64
	global_load_dwordx4 v[124:127], v[0:1], off offset:96
	s_cmp_lt_i32 s3, 18
	s_cselect_b32 s6, -9, 0xffffffee
	s_cmp_lt_i32 s3, 9
	s_cselect_b64 s[36:37], -1, 0
	s_and_b64 s[0:1], s[36:37], exec
	s_cselect_b32 s0, 0, s6
	v_and_b32_e32 v147, 63, v141
	s_add_i32 s0, s0, s3
	v_lshl_or_b32 v2, s0, 6, v147
	v_mul_hi_i32 v0, v2, s91
	v_lshrrev_b32_e32 v1, 31, v0
	v_ashrrev_i32_e32 v0, 1, v0
	v_add_u32_e32 v0, v0, v1
	v_mad_u64_u32 v[2:3], s[0:1], v0, -9, v[2:3]
	s_cmp_gt_i32 s3, 17
	v_min_i32_e32 v1, 7, v2
	s_mov_b64 s[0:1], -1
	s_cbranch_scc0 .LBB0_600
	s_cmp_lt_u32 s3, 36
	v_mul_lo_u32 v2, v0, s70
	v_lshl_add_u32 v2, v1, 4, v2
	s_cselect_b64 vcc, -1, 0
	v_cndmask_b32_e32 v176, 0, v2, vcc
	s_mov_b64 s[0:1], 0

.LBB0_654:
	v_readlane_b32 s0, v255, 24
	s_cmpk_gt_i32 s0, 0x3ff
	s_cbranch_scc1 .LBB0_715
	v_readlane_b32 s0, v255, 22
	v_readlane_b32 s1, v255, 23
	s_add_u32 s2, s0, 0x1c900180
	v_writelane_b32 v255, s2, 33
	s_addc_u32 s2, s1, 0
	v_writelane_b32 v255, s2, 26
	s_lshl_b32 s2, s8, 4
	v_readlane_b32 s89, v255, 24
	s_lshl_b32 s87, s89, 4
	v_writelane_b32 v255, s2, 27
	s_add_u32 s0, s0, 0x13a20880
	v_writelane_b32 v255, s0, 28
	s_addc_u32 s0, s1, 0
	v_writelane_b32 v255, s0, 29
	s_lshl_b32 s0, s8, 7
	s_lshl_b32 s90, s89, 7
	v_writelane_b32 v255, s0, 30
	s_mov_b32 s0, 0
	s_nop 0
	v_writelane_b32 v255, s0, 40
	s_branch .LBB0_657

.LBB0_657:
	s_bfe_u32 s2, s89, 0x30004
	v_mov_b32_e32 v141, v210
	s_mul_i32 s6, s2, 0x104
	v_readfirstlane_b32 s4, v141
	v_readlane_b32 s0, v255, 40
	s_cmp_lg_u32 s0, 0
	s_cbranch_scc1 .Lattn_bt_skip_s
	s_mov_b32 s0, 1
	s_nop 0
	v_writelane_b32 v255, s0, 40
	s_movk_i32 s0, 0x1c0
	v_cmp_gt_i32_e32 vcc, s0, v141
	s_and_saveexec_b64 s[0:1], vcc
	s_cbranch_execz .LBB0_659
	v_lshl_add_u32 v0, v141, 2, 0
	v_add_u32_e32 v2, 0x20000, v0
	v_add_u32_e32 v0, 0xffffffa0, v141
	v_max_i32_e32 v0, 0, v0
	v_min_i32_e32 v0, 0x100, v0
	v_add_u32_e32 v0, s6, v0
	v_readlane_b32 s8, v255, 22
	v_ashrrev_i32_e32 v1, 31, v0
	v_readlane_b32 s9, v255, 23
	s_nop 1
	v_lshl_add_u64 v[0:1], v[0:1], 2, s[8:9]
	global_load_dword v0, v[0:1], off
	s_waitcnt vmcnt(0)
	ds_write_b32 v2, v0

.Lattn_bt_skip_s:
	s_lshl_b32 s0, s89, 4
	s_and_b32 s0, s0, 0xfffff800
	s_add_i32 s34, s0, 0x2000
	s_lshl_b32 s0, s89, 7
	s_and_b32 s5, s0, 0x780
	s_ashr_i32 s3, s4, 6
	s_lshl_b32 s0, s6, 2
	s_and_b32 s95, s3, 3
	v_and_b32_e32 v140, 31, v141
	v_mov_b32_e32 v2, s0
	s_or_b32 s0, s34, s5
	s_lshl_b32 s88, s95, 5
	v_or_b32_e32 v0, s0, v140
	v_or_b32_e32 v3, s88, v0
	v_mov_b64_e32 v[0:1], s[18:19]
	s_ashr_i32 s83, s4, 8
	v_mad_i64_i32 v[0:1], s[0:1], v3, s81, v[0:1]
	s_lshl_b32 s72, s2, 8
	s_lshl_b32 s0, s83, 6
	v_lshl_add_u64 v[0:1], v[0:1], 0, s[72:73]
	s_ashr_i32 s1, s0, 31
	v_bfe_u32 v158, v141, 5, 1
	v_lshl_add_u64 v[0:1], s[0:1], 1, v[0:1]
	v_readlane_b32 s0, v255, 22
	v_lshlrev_b32_e32 v146, 4, v158
	v_mov_b32_e32 v147, v177
	v_readlane_b32 s1, v255, 23
	v_lshl_add_u64 v[0:1], v[0:1], 0, v[146:147]
	s_nop 3
	global_load_dword v159, v2, s[0:1]
	global_load_dword v160, v2, s[0:1] offset:1024
	global_load_dwordx4 v[112:115], v[0:1], off
	global_load_dwordx4 v[116:119], v[0:1], off offset:32
	global_load_dwordx4 v[120:123], v[0:1], off offset:64
	global_load_dwordx4 v[124:127], v[0:1], off offset:96
	s_cmp_lt_i32 s3, 18
	s_cselect_b32 s6, -9, 0xffffffee
	s_cmp_lt_i32 s3, 9
	s_cselect_b64 s[36:37], -1, 0
	s_and_b64 s[0:1], s[36:37], exec
	s_cselect_b32 s0, 0, s6
	v_and_b32_e32 v147, 63, v141
	s_add_i32 s0, s0, s3
	v_lshl_or_b32 v2, s0, 6, v147
	v_mul_hi_i32 v0, v2, s91
	v_lshrrev_b32_e32 v1, 31, v0
	v_ashrrev_i32_e32 v0, 1, v0
	v_add_u32_e32 v0, v0, v1
	v_mad_u64_u32 v[2:3], s[0:1], v0, -9, v[2:3]
	s_cmp_gt_i32 s3, 17
	v_min_i32_e32 v1, 7, v2
	s_mov_b64 s[0:1], -1
	s_cbranch_scc0 .LBB0_661
	s_cmp_lt_u32 s3, 36
	v_mul_lo_u32 v2, v0, s70
	v_lshl_add_u32 v2, v1, 4, v2
	s_cselect_b64 vcc, -1, 0
	v_cndmask_b32_e32 v176, 0, v2, vcc
	s_mov_b64 s[0:1], 0
